# split-phase grid barrier between P3 scans and P4: arrive after the scans, wait after the Hyena long conv (independent of the scan results)
# speedup vs baseline: 1.0114x; 1.0022x over previous
;     __device__ __forceinline__ float* fp(size_t off) const { return (float*)(ws + off); }
; __device__ __forceinline__ void hy_conv_item(const Ctx& C, int l, int c) {
;     const int tid = C.tid, lane = C.lane, w = C.wave;
;     bf16_t* G10 = (bf16_t*)C.lds; bf16_t* G11 = G10 + GLEN; bf16_t* G20 = G11 + GLEN; bf16_t* G21 = G20 + GLEN; bf16_t* U = G21 + GLEN;
;     float* red = (float*)(C.lds + (size_t)(4 * GLEN + 8 * UP) * 2); float* w3s = red + 64;
;     for (int i = tid; i < 2 * GLEN; i += NTHR) ((unsigned*)G10)[i] = 0u;
;     if (tid < 256) { const int q = tid >> 6, j = tid & 63; const int col = (q >> 1) * 512 + (q & 1) * 256 + c; w3s[q * 64 + j] = C.P->in[19][((size_t)l * 64 + j) * 1024 + col]; }
;     __syncthreads();
;     float ss[4] = {0.f, 0.f, 0.f, 0.f};
;     const float adelta = 3.0701134573253945f + (float)c * ((15.350567286626972f - 3.0701134573253945f) / 255.f);
;     const float* hdn = C.fp(OFF_HDN);
;     float* hft = (float*)U;
; #pragma unroll 1
;     for (int k = 0; k < 8; ++k) { const int t = tid + NTHR * k; const f32x4* hr = (const f32x4*)(hdn + (size_t)t * 64);
;         float a0 = 0.f, a1 = 0.f, a2 = 0.f, a3 = 0.f;
; #pragma unroll 1
;         for (int j8 = 0; j8 < 16; j8 += 8) {
;         f32x4 hrow[8];
; #pragma unroll
;         for (int j4 = 0; j4 < 8; ++j4) hrow[j4] = hr[j8 + j4];
; #pragma unroll
;         for (int jj4 = 0; jj4 < 8; ++jj4) { const f32x4 hv = hrow[jj4]; const int j4 = j8 + jj4;
;             const f32x4 q0 = *(const f32x4*)(w3s + 4 * j4), q1 = *(const f32x4*)(w3s + 64 + 4 * j4), q2 = *(const f32x4*)(w3s + 128 + 4 * j4), q3 = *(const f32x4*)(w3s + 192 + 4 * j4);
;             a0 += hv.x * q0.x + hv.y * q0.y + hv.z * q0.z + hv.w * q0.w; a1 += hv.x * q1.x + hv.y * q1.y + hv.z * q1.z + hv.w * q1.w;
;             a2 += hv.x * q2.x + hv.y * q2.y + hv.z * q2.z + hv.w * q2.w; a3 += hv.x * q3.x + hv.y * q3.y + hv.z * q3.z + hv.w * q3.w; } }
;         const float dec = __expf(-((float)t / 4095.f) * adelta);
;         a0 *= dec; a1 *= dec; a2 *= dec; a3 *= dec;
;         hft[t] = a0; hft[4096 + t] = a1; hft[8192 + t] = a2; hft[12288 + t] = a3;
;         ss[0] += a0 * a0; ss[1] += a1 * a1; ss[2] += a2 * a2; ss[3] += a3 * a3; }
; #pragma unroll
;     for (int q = 0; q < 4; ++q) { const float s_ = wave_sum(ss[q]); if (lane == 0) red[w * 4 + q] = s_; }
;     __syncthreads();
;     float sc[4];
; #pragma unroll
.Lmy_gs_poll_4:
.LBB0_602:
	s_or_b64 exec, exec, s[0:1]
	s_waitcnt lgkmcnt(0)
	v_mov_b32_e32 v0, v224
	s_mov_b64 s[0:1], 0
	v_readlane_b32 s6, v253, 28
	s_barrier
	v_mov_b32_e32 v114, v224
	v_readlane_b32 s7, v253, 29
	s_mov_b64 s[0:1], 0
	v_readfirstlane_b32 s4, v114
	s_and_b64 vcc, exec, s[6:7]
	s_cbranch_vccz .LBB0_639
	v_and_b32_e32 v0, 63, v114
	s_ashr_i32 s8, s4, 6
	s_movk_i32 s4, 0x4400
	v_cmp_gt_i32_e64 s[42:43], s4, v114
	s_movk_i32 s4, 0x100
	v_lshlrev_b32_e32 v1, 10, v114
	v_cmp_eq_u32_e64 s[46:47], 0, v0
	v_lshlrev_b32_e32 v0, 3, v114
	v_cmp_gt_i32_e64 s[44:45], s4, v114
	v_and_b32_e32 v1, 0xfc00, v1
	v_readlane_b32 s4, v254, 59
	v_and_b32_e32 v16, 0xff8, v0
	v_ashrrev_i32_e32 v0, 9, v114
	v_lshl_or_b32 v64, s4, 16, v1
	v_ashrrev_i32_e32 v1, 31, v0
	v_lshlrev_b64 v[90:91], 13, v[0:1]
	v_add_u32_e32 v1, 0x200, v114
	v_ashrrev_i32_e32 v2, 9, v1
	v_add_u32_e32 v1, 0x400, v114
	v_ashrrev_i32_e32 v4, 9, v1
	v_add_u32_e32 v1, 0x600, v114
	v_ashrrev_i32_e32 v6, 9, v1
	v_add_u32_e32 v1, 0x800, v114
	v_ashrrev_i32_e32 v8, 9, v1
	v_add_u32_e32 v1, 0xa00, v114
	v_ashrrev_i32_e32 v10, 9, v1
	v_add_u32_e32 v1, 0xc00, v114
	v_ashrrev_i32_e32 v12, 9, v1
	v_add_u32_e32 v1, 0xe00, v114
	v_ashrrev_i32_e32 v14, 9, v1
	v_sub_u32_e32 v1, 0x11f0, v16
	v_mul_i32_i24_e32 v0, 0x2810, v0
	v_lshlrev_b32_e32 v1, 1, v1
	v_readlane_b32 s10, v254, 37
	s_add_u32 s0, s24, s0
	s_addc_u32 s1, s25, s1
	v_add3_u32 v118, s10, v0, v1
	v_mul_i32_i24_e32 v0, 0x2810, v2
	v_add3_u32 v119, s10, v0, v1
	v_mul_i32_i24_e32 v0, 0x2810, v4
	v_add3_u32 v120, s10, v0, v1
	v_mul_i32_i24_e32 v0, 0x2810, v6
	v_readlane_b32 s5, v254, 60
	s_add_u32 s4, s0, 0x1e780000
	v_add3_u32 v121, s10, v0, v1
	v_mul_i32_i24_e32 v0, 0x2810, v8
	s_addc_u32 s5, s1, 0
	s_lshl_b32 s12, s8, 4
	s_movk_i32 s6, 0x5020
	v_add3_u32 v122, s10, v0, v1
	v_mul_i32_i24_e32 v0, 0x2810, v10
	v_cmp_gt_i32_e64 s[48:49], s6, v114
	s_add_u32 s6, s0, 0x17000000
	v_add3_u32 v123, s10, v0, v1
	v_mul_i32_i24_e32 v0, 0x2810, v12
	s_addc_u32 s7, s1, 0
	v_ashrrev_i32_e32 v3, 31, v2
	v_add3_u32 v124, s10, v0, v1
	v_mul_i32_i24_e32 v0, 0x2810, v14
	s_lshl_b32 s8, s8, 9
	v_lshlrev_b64 v[92:93], 13, v[2:3]
	v_add3_u32 v125, s10, v0, v1
	v_lshrrev_b32_e32 v0, 2, v114
	v_and_or_b32 v2, v114, 31, s8
	v_and_b32_e32 v0, 8, v0
	v_add_u32_e32 v2, 0xf9, v2
	v_ashrrev_i32_e32 v5, 31, v4
	v_sub_u32_e32 v3, v2, v0
	v_and_b32_e32 v2, 1, v2
	s_add_i32 s9, 0, 0x4400
	v_lshlrev_b64 v[94:95], 13, v[4:5]
	v_mov_b32_e32 v4, s9
	v_cmp_eq_u32_e32 vcc, 0, v2
	v_and_b32_e32 v3, 0x7ffffffe, v3
	v_lshlrev_b32_e32 v3, 1, v3
	v_cndmask_b32_e64 v2, v4, 0, vcc
	v_lshlrev_b32_e32 v4, 5, v114
	v_bfe_u32 v1, v114, 2, 3
	v_add_u32_e32 v126, v2, v3
	v_mov_b32_e32 v2, s10
	s_movk_i32 s9, 0x2810
	v_and_b32_e32 v4, 0x60, v4
	v_readlane_b32 s68, v251, 36
	v_mad_u32_u24 v2, v1, s9, v2
	v_sub_u32_e32 v0, v4, v0
	v_readlane_b32 s74, v251, 42
	v_readlane_b32 s75, v251, 43
	v_lshl_add_u32 v127, v0, 1, v2
	v_lshrrev_b32_e32 v0, 3, v114
	v_lshl_add_u64 v[86:87], v[64:65], 2, s[74:75]
	v_lshlrev_b32_e32 v64, 1, v16
	v_ashrrev_i32_e32 v7, 31, v6
	v_and_b32_e32 v5, 4, v0
	v_lshl_add_u64 v[88:89], s[6:7], 0, v[64:65]
	v_lshlrev_b64 v[96:97], 13, v[6:7]
	v_lshlrev_b32_e32 v64, 13, v1
	v_or_b32_e32 v6, s8, v5
	v_lshl_add_u64 v[0:1], s[6:7], 0, v[64:65]
	v_sub_u32_e32 v6, v4, v6
	v_readlane_b32 s6, v254, 39
	v_lshl_add_u32 v128, v6, 1, v2
	v_xor_b32_e32 v7, 1, v221
	v_mov_b32_e32 v2, s6
	v_readlane_b32 s6, v254, 38
	s_ashr_i32 s9, s8, 31
	v_lshlrev_b32_e32 v115, 2, v114
	v_mov_b32_e32 v6, s6
	v_cndmask_b32_e32 v2, v2, v6, vcc
	v_and_b32_e32 v6, 64, v221
	v_add_u32_e32 v6, 64, v6
	v_cmp_lt_i32_e32 vcc, v7, v6
	v_add_u32_e32 v129, v2, v3
	v_lshl_add_u64 v[2:3], s[0:1], 0, v[64:65]
	v_cndmask_b32_e32 v7, v221, v7, vcc
	v_lshlrev_b32_e32 v64, 2, v7
	v_xor_b32_e32 v7, 2, v221
	v_cmp_lt_i32_e32 vcc, v7, v6
	v_ashrrev_i32_e32 v9, 31, v8
	v_ashrrev_i32_e32 v11, 31, v10
	v_cndmask_b32_e32 v7, v221, v7, vcc
	v_lshlrev_b32_e32 v130, 2, v7
	v_xor_b32_e32 v7, 4, v221
	v_cmp_lt_i32_e32 vcc, v7, v6
	v_ashrrev_i32_e32 v13, 31, v12
	v_ashrrev_i32_e32 v15, 31, v14
	v_cndmask_b32_e32 v7, v221, v7, vcc
	v_lshlrev_b32_e32 v131, 2, v7
	v_xor_b32_e32 v7, 8, v221
	v_cmp_lt_i32_e32 vcc, v7, v6
	v_and_b32_e32 v116, 0xffffff00, v115
	v_add_u32_e32 v117, s61, v115
	v_cndmask_b32_e32 v7, v221, v7, vcc
	v_lshlrev_b32_e32 v132, 2, v7
	v_xor_b32_e32 v7, 16, v221
	v_cmp_lt_i32_e32 vcc, v7, v6
	v_lshlrev_b64 v[98:99], 13, v[8:9]
	v_lshlrev_b64 v[100:101], 13, v[10:11]
	v_cndmask_b32_e32 v7, v221, v7, vcc
	v_lshlrev_b32_e32 v133, 2, v7
	v_xor_b32_e32 v7, 32, v221
	v_cmp_lt_i32_e32 vcc, v7, v6
	v_lshlrev_b64 v[102:103], 13, v[12:13]
	v_lshlrev_b64 v[104:105], 13, v[14:15]
	v_cndmask_b32_e32 v6, v221, v7, vcc
	v_sub_co_u32_e32 v4, vcc, v5, v4
	v_lshlrev_b32_e32 v134, 2, v6
	s_nop 0
	v_subb_co_u32_e64 v5, s[0:1], 0, 0, vcc
	v_lshl_add_u64 v[4:5], v[4:5], 0, s[8:9]
	v_lshlrev_b64 v[4:5], 1, v[4:5]
	v_lshl_add_u64 v[106:107], v[0:1], 0, v[4:5]
	v_lshl_add_u64 v[0:1], v[2:3], 0, v[4:5]
	s_mov_b64 s[0:1], 0x1eb04000
	v_lshl_add_u64 v[108:109], v[0:1], 0, s[0:1]
	v_lshlrev_b32_e32 v0, 1, v114
	v_add_u32_e32 v135, 0, v115
	v_add_u32_e32 v136, 0xfffffe00, v114
	v_sub_u32_e32 v137, 0x2200, v0
	v_add_u32_e32 v138, 0x2200, v0
	v_sub_u32_e32 v139, 0, v114
	v_add_u32_e32 v140, s10, v115
	s_mov_b32 s6, s90
	v_readlane_b32 s69, v251, 37
	v_readlane_b32 s70, v251, 38
	v_readlane_b32 s71, v251, 39
	v_readlane_b32 s72, v251, 40
	v_readlane_b32 s73, v251, 41
	v_readlane_b32 s76, v251, 44
	v_readlane_b32 s77, v251, 45
	v_readlane_b32 s78, v251, 46
	v_readlane_b32 s79, v251, 47
	v_readlane_b32 s80, v251, 48
	v_readlane_b32 s81, v251, 49
	v_readlane_b32 s82, v251, 50
	v_readlane_b32 s83, v251, 51
	s_branch .LBB0_606

; #define FRESH() do { int _t = threadIdx.x; asm volatile("" : "+v"(_t)); C.tid = _t; C.lane = _t & 63; C.wave = __builtin_amdgcn_readfirstlane(_t >> 6); size_t _z = 0; asm volatile("" : "+s"(_z)); C.ws = prm.ws + _z; C.out = prm.out + _z; } while (0)
; __global__ void __launch_bounds__(NTHR, 2) fwd_megakernel(Params prm) {
;     ...
;         FRESH();
;         for (int _m = 0; _m < REP_HYC; ++_m) for (int c = bid; c < 256; c += G) hy_conv_item(C, l, c);
;         __syncthreads();
;         FRESH();
;         for (int _m = 0; _m < REP_MIXB; ++_m) for (int it = bid * 8 + C.wave; it < 1024; it += G * 8) hgrn_pass3_item<1>(C, l, it);
.LBB0_639:
	s_mov_b64 s[4:5], exec
	v_readlane_b32 s6, v251, 2
	v_readlane_b32 s7, v251, 3
	s_and_b64 s[6:7], s[4:5], s[6:7]
	s_mov_b64 exec, s[6:7]
	s_cbranch_execz .Lmy_w4_end
	v_readlane_b32 s8, v255, 51
	s_add_u32 s10, s24, 0x1eb03c00
	s_addc_u32 s11, s25, 0
	v_mov_b32_e32 v1, 0
.Lmy_w4_poll:
	global_load_dword v0, v1, s[10:11] sc1
	s_waitcnt vmcnt(0)
	v_cmp_gt_u32_e32 vcc, s8, v0
	s_cbranch_vccz .Lmy_w4_done
	s_sleep 2
	s_branch .Lmy_w4_poll

;     __device__ __forceinline__ float* fp(size_t off) const { return (float*)(ws + off); }
; __device__ __forceinline__ void hgrn_state_load(const float* sb, f32x4 (&Sacc)[4][4], int fr, int quad) {
; #pragma unroll
;     for (int kt = 0; kt < 4; ++kt)
; #pragma unroll
;         for (int vt = 0; vt < 4; ++vt)
; #pragma unroll
;             for (int r = 0; r < 4; ++r) Sacc[kt][vt][r] = sb[(16 * kt + 4 * quad + r) * 64 + 16 * vt + fr];
; }
; template <int DIR>
; __device__ __forceinline__ void hgrn_pass3_item(const Ctx& C, int l, int item) {
;     const int c = item & 31, hd = (item >> 5) & 3, b = item >> 7;
;     unsigned char* wl = C.lds + C.wave * 14336;
;     const float lb = hgrn_lb(C, l, hd * 64 + C.lane);
;     const int fr = C.lane & 15, quad = C.lane >> 4;
;     f32x4 Sacc[4][4]; float dectot = 1.f;
;     if (DIR == 1) {
;         hgrn_state_load(C.fp(OFF_S) + (size_t)((((1 * 8 + b) * 4 + hd) * 32) + (31 - c)) * 4096, Sacc, fr, quad);
;         hgrn_mfma<1>(C, l, 1, b, hd, 31 - c, Sacc, dectot, wl, lb);
.Lmy_w4_end:
	s_or_b64 exec, exec, s[4:5]
	v_mov_b32_e32 v0, v224
	s_barrier
	v_readlane_b32 s5, v253, 32
	v_readfirstlane_b32 s0, v0
	s_ashr_i32 s4, s0, 6
	s_add_i32 s48, s4, s5
	s_mov_b64 s[0:1], 0
	s_cmpk_gt_i32 s48, 0x3ff
	v_readlane_b32 s40, v255, 7
	s_cbranch_scc1 .LBB0_648
	v_bfe_u32 v3, v0, 4, 2
	v_and_b32_e32 v1, 15, v0
	v_lshlrev_b32_e32 v5, 8, v3
	v_or_b32_e32 v7, 16, v1
	v_or_b32_e32 v9, 32, v1
	v_or_b32_e32 v11, 48, v1
	v_or_b32_e32 v15, 0x440, v5
	v_or_b32_e32 v6, v15, v1
	v_or_b32_e32 v17, 0x480, v5
	v_or_b32_e32 v14, v15, v7
	v_or_b32_e32 v22, v15, v9
	v_or_b32_e32 v30, v15, v11
	v_or_b32_e32 v15, 0x840, v5
	s_add_u32 s0, s24, s0
	s_mulk_i32 s4, 0x3800
	v_or_b32_e32 v13, 0x400, v5
	v_or_b32_e32 v8, v17, v1
	v_or_b32_e32 v16, v17, v7
	v_or_b32_e32 v24, v17, v9
	v_or_b32_e32 v32, v17, v11
	v_or_b32_e32 v38, v15, v1
	v_or_b32_e32 v17, 0x880, v5
	v_or_b32_e32 v46, v15, v7
	v_or_b32_e32 v54, v15, v9
	v_or_b32_e32 v62, v15, v11
	v_or_b32_e32 v15, 0xc40, v5
	s_addc_u32 s1, s25, s1
	s_add_i32 s49, s4, 0
	v_or_b32_e32 v4, v13, v1
	v_or_b32_e32 v12, v13, v7
	v_or_b32_e32 v20, v13, v9
	v_or_b32_e32 v28, v13, v11
	v_or_b32_e32 v13, 0x800, v5
	v_or_b32_e32 v40, v17, v1
	v_or_b32_e32 v48, v17, v7
	v_or_b32_e32 v56, v17, v9
	v_or_b32_e32 v66, v17, v11
	v_or_b32_e32 v72, v15, v1
	v_or_b32_e32 v17, 0xc80, v5
	v_or_b32_e32 v80, v15, v7
	v_or_b32_e32 v88, v15, v9
	v_or_b32_e32 v96, v15, v11
	v_lshlrev_b32_e32 v120, 2, v3
	v_lshlrev_b32_e32 v121, 3, v3
	v_bfe_u32 v15, v0, 2, 2
	s_add_u32 s53, s0, 0x1a180000
	v_or_b32_e32 v19, 0x4c0, v5
	v_or_b32_e32 v36, v13, v1
	v_or_b32_e32 v44, v13, v7
	v_or_b32_e32 v52, v13, v9
	v_or_b32_e32 v60, v13, v11
	v_or_b32_e32 v13, 0xc00, v5
	v_or_b32_e32 v74, v17, v1
	v_or_b32_e32 v82, v17, v7
	v_or_b32_e32 v90, v17, v9
	v_or_b32_e32 v98, v17, v11
	v_mul_u32_u24_e32 v3, 0x48, v1
	v_or_b32_e32 v17, v120, v15
	v_or_b32_e32 v15, v121, v15
	v_and_b32_e32 v118, 63, v0
	s_addc_u32 s68, s1, 0
	v_or_b32_e32 v10, v19, v1
	v_or_b32_e32 v18, v19, v7
	v_or_b32_e32 v26, v19, v9
	v_or_b32_e32 v34, v19, v11
	v_or_b32_e32 v19, 0x8c0, v5
	v_or_b32_e32 v70, v13, v1
	v_or_b32_e32 v78, v13, v7
	v_or_b32_e32 v86, v13, v9
	v_or_b32_e32 v94, v13, v11
	v_lshlrev_b32_e32 v3, 1, v3
	v_and_b32_e32 v13, 48, v0
	v_lshlrev_b32_e32 v0, 3, v0
	v_mul_u32_u24_e32 v15, 0x48, v15
	v_or_b32_e32 v42, v19, v1
	v_or_b32_e32 v50, v19, v7
	v_or_b32_e32 v58, v19, v9
	v_or_b32_e32 v68, v19, v11
	v_or_b32_e32 v19, 0xcc0, v5
	s_add_u32 s69, s0, 0x7000000
	v_add3_u32 v123, s49, v3, v13
	v_sub_u32_e32 v13, v1, v120
	v_mul_u32_u24_e32 v17, 0x90, v17
	v_and_b32_e32 v0, 24, v0
	v_lshlrev_b32_e32 v15, 1, v15
	v_lshlrev_b32_e32 v64, 1, v1
	v_or_b32_e32 v2, v5, v1
	v_or_b32_e32 v76, v19, v1
	s_addc_u32 s70, s1, 0
	v_add3_u32 v124, s49, v17, v0
	v_add3_u32 v125, s49, v15, v0
	v_lshl_add_u64 v[0:1], s[0:1], 0, v[64:65]
	s_mov_b64 s[0:1], 0x4000000
	v_cmp_gt_i32_e64 s[4:5], 2, v13
	v_cmp_gt_i32_e64 s[42:43], 3, v13
	v_lshl_add_u64 v[114:115], v[0:1], 0, s[0:1]
	v_cmp_gt_i32_e64 s[0:1], 1, v13
	s_and_b64 s[20:21], s[42:43], s[4:5]
	v_or_b32_e32 v84, v19, v7
	v_or_b32_e32 v92, v19, v9
	v_or_b32_e32 v100, v19, v11
	v_add_u32_e32 v122, s49, v121
	v_cmp_gt_i32_e32 vcc, 0, v13
	v_or_b32_e32 v0, v5, v7
	v_or_b32_e32 v64, v5, v9
	v_or_b32_e32 v102, v5, v11
	s_and_b64 s[38:39], s[20:21], s[0:1]
	v_lshl_add_u32 v119, v118, 2, s49
	v_add_u32_e32 v126, v122, v3
	v_lshlrev_b32_e32 v127, 2, v2
	v_lshlrev_b32_e32 v128, 2, v0
	v_lshlrev_b32_e32 v129, 2, v64
	v_lshlrev_b32_e32 v130, 2, v102
	v_lshlrev_b32_e32 v131, 2, v4
	v_lshlrev_b32_e32 v132, 2, v6
	v_lshlrev_b32_e32 v133, 2, v8
	v_lshlrev_b32_e32 v134, 2, v10
	v_lshlrev_b32_e32 v135, 2, v12
	v_lshlrev_b32_e32 v136, 2, v14
	v_lshlrev_b32_e32 v137, 2, v16
	v_lshlrev_b32_e32 v138, 2, v18
	v_lshlrev_b32_e32 v139, 2, v20
	v_lshlrev_b32_e32 v140, 2, v22
	v_lshlrev_b32_e32 v141, 2, v24
	v_lshlrev_b32_e32 v142, 2, v26
	v_lshlrev_b32_e32 v143, 2, v28
	v_lshlrev_b32_e32 v144, 2, v30
	v_lshlrev_b32_e32 v145, 2, v32
	v_lshlrev_b32_e32 v146, 2, v34
	v_lshlrev_b32_e32 v147, 2, v36
	v_lshlrev_b32_e32 v148, 2, v38
	v_lshlrev_b32_e32 v149, 2, v40
	v_lshlrev_b32_e32 v150, 2, v42
	v_lshlrev_b32_e32 v151, 2, v44
	v_lshlrev_b32_e32 v152, 2, v46
	v_lshlrev_b32_e32 v153, 2, v48
	v_lshlrev_b32_e32 v154, 2, v50
	v_lshlrev_b32_e32 v155, 2, v52
	v_lshlrev_b32_e32 v156, 2, v54
	v_lshlrev_b32_e32 v157, 2, v56
	v_lshlrev_b32_e32 v158, 2, v58
	v_lshlrev_b32_e32 v159, 2, v60
	v_lshlrev_b32_e32 v160, 2, v62
	v_lshlrev_b32_e32 v161, 2, v66
	v_lshlrev_b32_e32 v162, 2, v68
	v_lshlrev_b32_e32 v163, 2, v70
	v_lshlrev_b32_e32 v164, 2, v72
	v_lshlrev_b32_e32 v165, 2, v74
	v_lshlrev_b32_e32 v166, 2, v76
	v_lshlrev_b32_e32 v167, 2, v78
	v_lshlrev_b32_e32 v168, 2, v80
	v_lshlrev_b32_e32 v169, 2, v82
	v_lshlrev_b32_e32 v170, 2, v84
	v_lshlrev_b32_e32 v171, 2, v86
	v_lshlrev_b32_e32 v172, 2, v88
	v_lshlrev_b32_e32 v173, 2, v90
	v_lshlrev_b32_e32 v174, 2, v92
	v_lshlrev_b32_e32 v175, 2, v94
	v_lshlrev_b32_e32 v176, 2, v96
	v_lshlrev_b32_e32 v177, 2, v98
	v_lshlrev_b32_e32 v183, 2, v100
	s_and_b64 s[44:45], s[38:39], vcc
